# P8: the 88 workgroups that own a sample split-K unit run it first instead of last (unit order only), so their epilogues run out of phase with the other workgroups
# baseline (speedup 1.0000x reference)
; __device__ __forceinline__ int xcd_map(int L, int nwg) { const int q = nwg / NXCD, r = nwg % NXCD, xcd = L % NXCD, off = L / NXCD; return (xcd < r ? xcd * (q + 1) : r * (q + 1) + (xcd - r) * q) + off; }
;     __device__ __forceinline__ bool next(int i, Unit& u) const { const int L = i * G + c; if (L >= NTOT) return false; pg8::grouped(pg8::xcd_map(L, NTOT), NM, 3, u.pm, u.pn); u.kind = 0; return true; }
;     __device__ __forceinline__ bool next(int i, Unit& u) const { const int L = i * G + c; if (L >= NTOT) return false; pg8::grouped(pg8::xcd_map(L, NTOT), NM, NN, u.pm, u.pn); u.kind = 0; return true; }
;     __device__ __forceinline__ bool next(int i, Unit& u) const {
;         const int L = i * G + c; if (L >= 512 + 8 * nsk) return false;
;         int pm, pn; pg8::grouped(pg8::xcd_map(L < 512 ? L : 0, 512), 128, 4, pm, pn);
;         const int idx = L - 512, rem = idx & 7; const bool sp = L >= 512;
;         u.pm = sp ? 128 + (rem >> 2) : pm; u.pn = sp ? (rem & 3) : pn; u.kind = sp ? 1 + (idx >> 3) : 0;
;         return true;
.LBB0_1236:
	s_or_b64 exec, exec, s[0:1]
	v_mov_b32_e32 v8, v211
	s_waitcnt lgkmcnt(0)
	s_barrier
	s_mov_b32 s98, s2
	s_cmpk_lt_i32 s2, 0x58
	s_cbranch_scc0 .Lp8_l0
	s_addk_i32 s98, 0x200
.Lp8_l0:
	s_cmpk_gt_i32 s98, 0x257
	v_readfirstlane_b32 s10, v8
	s_cbranch_scc1 .LBB0_1268
	s_cmpk_lt_i32 s98, 0x200
	s_cselect_b64 s[0:1], -1, 0
	s_and_b64 s[8:9], s[0:1], exec
	s_cselect_b32 s7, s98, 0
	s_ashr_i32 s8, s7, 31
	s_lshr_b32 s8, s8, 29
	s_add_i32 s11, s7, s8
	s_and_b32 s8, s11, -8
	s_sub_i32 s7, s7, s8
	s_cmp_gt_i32 s7, -1
	s_cbranch_scc0 .LBB0_1239
	s_lshl_b32 s14, s7, 6
	s_ashr_i32 s8, s11, 3
	s_cbranch_execz .LBB0_1240
	s_branch .LBB0_1241

; __device__ __forceinline__ int xcd_map(int L, int nwg) { const int q = nwg / NXCD, r = nwg % NXCD, xcd = L % NXCD, off = L / NXCD; return (xcd < r ? xcd * (q + 1) : r * (q + 1) + (xcd - r) * q) + off; }
; template <class Prog>
; __device__ __forceinline__ void gemm_phase(LAS unsigned char* lds, const Prog& P) {
;     ...
;     for (int i = 0; i < 2; ++i) { int R, C; stage_rc(tid * 16 + i * 8192, R, C); const int Rb = (R & ~31) + perm32(R & 31);
;         voffA[i] = (unsigned)(R * lda + C) * 2u; voffB[i] = (unsigned)(Rb * ldb + C) * 2u; }
;     const size_t kstep = (size_t)(BK * 2);
;     const size_t hstepA = (size_t)HALF * lda * 2, hstepB = (size_t)HALF * ldb * 2;
;     const unsigned ldsw = (unsigned)wid * 1024u;
;     const int aoff = lds_byte(wr * 64 + fr, fq * 8), boff = lds_byte(wc * 32 + fr, fq * 8);
;     ...
;     Unit cur, nxt; int ui = 0;
;     if (!P.next(0, cur)) return;
;     f32x4 acc[2][2][4][2];
; #pragma unroll
;     for (int a = 0; a < 2; ++a)
; #pragma unroll
;         for (int b = 0; b < 2; ++b)
; #pragma unroll
;             for (int m = 0; m < 4; ++m)
; #pragma unroll
;                 for (int n = 0; n < 2; ++n) acc[a][b][m][n] = (f32x4){0.f, 0.f, 0.f, 0.f};
;     bf16x8 At[4][2], B0[2][2], B1[2][2];
;     const char* cA = P.aptr(cur); const char* cB = P.bptr(cur);
;     PG8_STAGE(PG8_SB(0, 0), cB, voffB); PG8_STAGE(PG8_SB(0, 1), cB + hstepB, voffB); PG8_STAGE(PG8_SA(0, 0), cA, voffA); PG8_STAGE(PG8_SA(0, 1), cA + hstepA, voffA);
;     if (wr == 1) PG8_BAR;
;     PG8_WAIT_V(2); PG8_BAR;
;     PG8_STAGE(PG8_SB(1, 0), cB + kstep, voffB); PG8_STAGE(PG8_SA(1, 0), cA + kstep, voffA); PG8_STAGE(PG8_SB(1, 1), cB + hstepB + kstep, voffB);
;     PG8_WAIT_V(6); PG8_BAR;
;     __device__ __forceinline__ bool next(int i, Unit& u) const {
;     ...
;         int pm, pn; pg8::grouped(pg8::xcd_map(L < 512 ? L : 0, 512), 128, 4, pm, pn);
;         const int idx = L - 512, rem = idx & 7; const bool sp = L >= 512;
;         u.pm = sp ? 128 + (rem >> 2) : pm; u.pn = sp ? (rem & 3) : pn; u.kind = sp ? 1 + (idx >> 3) : 0;
;         return true;
;     }
;     __device__ __forceinline__ const char* aptr(const Unit& u) const { return (const char*)(Ab + (size_t)u.pm * 256 * K + (u.kind ? (u.kind - 1) * 256 : 0)); }
;     __device__ __forceinline__ const char* bptr(const Unit& u) const { return (const char*)(Wt + (size_t)u.pn * 256 * K + (u.kind ? (u.kind - 1) * 256 : 0)); }
.LBB0_1241:
	v_ashrrev_i32_e32 v1, 31, v8
	v_lshrrev_b32_e32 v1, 26, v1
	v_add_u32_e32 v1, v8, v1
	v_ashrrev_i32_e32 v9, 6, v1
	v_bfe_i32 v1, v8, 27, 1
	v_lshlrev_b32_e32 v0, 4, v8
	v_lshrrev_b32_e32 v1, 22, v1
	v_add_u32_e32 v1, v0, v1
	v_and_b32_e32 v1, 0xfffffc00, v1
	v_sub_u32_e32 v1, v0, v1
	v_lshrrev_b32_e32 v2, 4, v1
	v_bitop3_b32 v2, v2, v1, 32 bitop3:0x6c
	v_ashrrev_i32_e32 v1, 31, v1
	v_lshrrev_b32_e32 v1, 26, v1
	v_lshlrev_b32_e32 v3, 3, v9
	v_add_u32_e32 v1, v2, v1
	v_and_b32_e32 v3, -16, v3
	v_ashrrev_i32_e32 v11, 6, v1
	v_add_u32_e32 v1, v11, v3
	v_lshlrev_b32_e32 v3, 5, v9
	v_and_b32_e32 v10, 32, v3
	v_mul_i32_i24_e32 v3, 64, v11
	v_sub_u32_e32 v2, v2, v3
	v_mov_b32_e32 v3, 1
	v_ashrrev_i16_sdwa v2, v3, sext(v2) dst_sel:DWORD dst_unused:UNUSED_PAD src0_sel:DWORD src1_sel:BYTE_0
	v_lshlrev_b32_e32 v4, 1, v1
	v_lshrrev_b32_e32 v5, 2, v1
	v_and_b32_e32 v6, 3, v11
	s_mov_b32 s7, 0xffffe0
	v_bfe_i32 v12, v2, 0, 16
	v_and_b32_e32 v4, 24, v4
	v_and_b32_e32 v5, 4, v5
	v_and_or_b32 v6, v1, s7, v6
	s_movk_i32 s11, 0xb00
	v_add_u32_e32 v2, v10, v12
	v_or3_b32 v4, v6, v5, v4
	v_mul_lo_u32 v1, v1, s11
	v_add_lshl_u32 v144, v2, v1, 1
	v_mul_u32_u24_e32 v1, 0xb00, v4
	v_add_u32_e32 v0, 0x2000, v0
	v_add_lshl_u32 v146, v1, v2, 1
	v_ashrrev_i32_e32 v1, 31, v0
	s_add_i32 s8, s14, s8
	v_lshrrev_b32_e32 v1, 22, v1
	s_ashr_i32 s9, s8, 31
	v_add_u32_e32 v1, v0, v1
	s_lshr_b32 s9, s9, 27
	v_ashrrev_i32_e32 v13, 10, v1
	s_add_i32 s9, s8, s9
	v_mul_i32_i24_e32 v1, 0x400, v13
	s_ashr_i32 s14, s9, 5
	s_and_b32 s9, s9, 0xffe0
	v_sub_u32_e32 v0, v0, v1
	s_sub_i32 s8, s8, s9
	v_lshrrev_b32_e32 v1, 4, v0
	s_bfe_i32 s9, s8, 0x80000
	v_bitop3_b32 v0, v1, v0, 32 bitop3:0x6c
	s_bfe_u32 s9, s9, 0x3000c
	v_ashrrev_i32_e32 v2, 31, v0
	s_add_i32 s9, s8, s9
	v_lshrrev_b32_e32 v2, 26, v2
	s_bfe_i32 s15, s9, 0x80000
	s_and_b32 s9, s9, 0xf8
	v_lshlrev_b32_e32 v1, 3, v13
	v_add_u32_e32 v2, v0, v2
	s_sub_i32 s8, s8, s9
	v_and_b32_e32 v1, -16, v1
	v_ashrrev_i32_e32 v14, 6, v2
	v_lshlrev_b32_e32 v4, 5, v13
	s_lshl_b32 s14, s14, 3
	s_sext_i32_i8 s8, s8
	v_add_u32_e32 v1, v14, v1
	v_and_b32_e32 v15, 32, v4
	v_and_b32_e32 v4, 3, v14
	s_ashr_i32 s13, s10, 6
	s_sext_i32_i16 s15, s15
	s_add_i32 s14, s14, s8
	s_bfe_u32 s8, s98, 0x10002
	s_ashr_i32 s12, s10, 8
	v_and_or_b32 v4, v1, s7, v4
	s_lshl_b32 s7, s13, 10
	s_ashr_i32 s15, s15, 3
	s_add_i32 s18, s98, 0xfffffe00
	s_or_b32 s19, s8, 0x80
	s_and_b64 s[8:9], s[0:1], exec
	s_cselect_b32 s59, s14, s19
	s_and_b32 s14, s98, 3
	s_and_b64 s[8:9], s[0:1], exec
	s_cselect_b32 s60, s15, s14
	s_lshr_b32 s8, s18, 3
	s_add_i32 s14, s8, 1
	s_and_b64 s[8:9], s[0:1], exec
	s_cselect_b32 s36, 0, s14
	s_lshl_b32 s8, s36, 8
	s_addk_i32 s8, 0xff00
	s_and_b64 s[0:1], s[0:1], exec
	s_cselect_b32 s0, 0, s8
	s_ashr_i32 s1, s0, 31
	s_mul_i32 s9, s59, 0x160000
	s_mul_hi_i32 s8, s59, 0x160000
	s_add_u32 s14, s16, s9
	s_addc_u32 s15, s17, s8
	s_mul_i32 s8, s60, 0xb0000
	s_ashr_i32 s9, s8, 31
	s_lshl_b64 s[8:9], s[8:9], 1
	v_readlane_b32 s18, v238, 44
	v_and_b32_e32 v2, 0xc0, v2
	v_readlane_b32 s19, v238, 45
	s_add_u32 s8, s18, s8
	v_sub_u32_e32 v0, v0, v2
	s_addc_u32 s9, s19, s9
	s_lshl_b64 s[0:1], s[0:1], 1
	v_ashrrev_i16_sdwa v0, v3, sext(v0) dst_sel:DWORD dst_unused:UNUSED_PAD src0_sel:DWORD src1_sel:BYTE_0
	v_lshlrev_b32_e32 v2, 1, v1
	v_lshrrev_b32_e32 v3, 2, v1
	s_add_u32 s42, s8, s0
	v_bfe_i32 v16, v0, 0, 16
	v_and_b32_e32 v2, 24, v2
	v_and_b32_e32 v3, 4, v3
	s_addc_u32 s43, s9, s1
	s_add_i32 s21, s7, 0
	v_add_u32_e32 v0, v15, v16
	v_or3_b32 v2, v4, v3, v2
	v_mul_lo_u32 v1, v1, s11
	s_add_i32 m0, s21, 0x10000
	v_add_lshl_u32 v148, v0, v1, 1
	v_mul_u32_u24_e32 v1, 0xb00, v2
	global_load_lds_dwordx4 v146, s[42:43]
	s_add_i32 m0, s21, 0x12000
	v_add_lshl_u32 v150, v1, v0, 1
	s_add_u32 s8, s42, 0xb0000
	global_load_lds_dwordx4 v150, s[42:43]
	s_addc_u32 s9, s43, 0
	s_add_i32 m0, s21, 0x14000
	v_mov_b32_e32 v147, 0
	global_load_lds_dwordx4 v146, s[8:9]
	s_add_i32 m0, s21, 0x16000
	s_add_u32 s40, s14, s0
	s_addc_u32 s41, s15, s1
	s_add_i32 s22, s21, 0x2000
	global_load_lds_dwordx4 v150, s[8:9]
	s_mov_b32 m0, s21
	s_add_u32 s0, s40, 0xb0000
	global_load_lds_dwordx4 v144, s[40:41]
	s_mov_b32 m0, s22
	s_addc_u32 s1, s41, 0
	s_add_i32 s23, s21, 0x4000
	global_load_lds_dwordx4 v148, s[40:41]
	s_mov_b32 m0, s23
	s_add_i32 s33, s21, 0x6000
	global_load_lds_dwordx4 v144, s[0:1]
	s_mov_b32 m0, s33
	v_mov_b32_e32 v151, v147
	global_load_lds_dwordx4 v148, s[0:1]
	v_mov_b32_e32 v145, v147
	v_mov_b32_e32 v149, v147
	s_cmp_eq_u32 s12, 1
	s_mov_b32 s46, 0
	v_lshl_add_u64 v[6:7], s[42:43], 0, v[146:147]
	v_lshl_add_u64 v[4:5], s[42:43], 0, v[150:151]
	v_lshl_add_u64 v[0:1], s[40:41], 0, v[144:145]
	s_cselect_b64 s[8:9], -1, 0
	s_cmp_lg_u32 s12, 1
	v_lshl_add_u64 v[2:3], s[40:41], 0, v[148:149]
	s_cbranch_scc1 .LBB0_1243
	s_barrier

; __device__ __forceinline__ int xcd_map(int L, int nwg) { const int q = nwg / NXCD, r = nwg % NXCD, xcd = L % NXCD, off = L / NXCD; return (xcd < r ? xcd * (q + 1) : r * (q + 1) + (xcd - r) * q) + off; }
;     __device__ __forceinline__ bool next(int i, Unit& u) const { const int L = i * G + c; if (L >= NTOT) return false; pg8::grouped(pg8::xcd_map(L, NTOT), NM, 3, u.pm, u.pn); u.kind = 0; return true; }
;     __device__ __forceinline__ bool next(int i, Unit& u) const { const int L = i * G + c; if (L >= NTOT) return false; pg8::grouped(pg8::xcd_map(L, NTOT), NM, NN, u.pm, u.pn); u.kind = 0; return true; }
;     __device__ __forceinline__ bool next(int i, Unit& u) const {
;         const int L = i * G + c; if (L >= 512 + 8 * nsk) return false;
;         int pm, pn; pg8::grouped(pg8::xcd_map(L < 512 ? L : 0, 512), 128, 4, pm, pn);
;         const int idx = L - 512, rem = idx & 7; const bool sp = L >= 512;
;         u.pm = sp ? 128 + (rem >> 2) : pm; u.pn = sp ? (rem & 3) : pn; u.kind = sp ? 1 + (idx >> 3) : 0;
;         return true;
.LBB0_1246:
	s_add_i32 s46, s46, 1
	s_mul_i32 s24, s46, s34
	s_add_i32 s24, s24, s2
	s_cmpk_lt_i32 s2, 0x58
	s_cbranch_scc0 .Lp8_l1
	s_addk_i32 s24, 0xff00
	s_cmp_lt_i32 s46, 3
	s_cselect_b32 s24, s24, 0x7fff
.Lp8_l1:
	s_cmpk_lt_i32 s24, 0x258
	s_cselect_b64 s[10:11], -1, 0
	s_cmpk_gt_i32 s24, 0x257
	s_cbranch_scc1 .LBB0_1252
	s_cmpk_lt_i32 s24, 0x200
	s_cselect_b32 s0, s24, 0
	s_ashr_i32 s1, s0, 31
	s_lshr_b32 s1, s1, 29
	s_add_i32 s25, s0, s1
	s_and_b32 s1, s25, -8
	s_sub_i32 s26, s0, s1
	s_cmp_gt_i32 s26, -1
	s_mov_b64 s[0:1], -1
	s_cbranch_scc0 .LBB0_1249
	s_lshl_b32 s27, s26, 6
	s_mov_b64 s[0:1], 0
